# v84 + tile-loop headers of ph_win/ph_gu: division by the constant group size 4 as shift/mask instead of the rcp-based generic division
# speedup vs baseline: 1.0121x; 1.0026x over previous
;     DI bool next(int i, Unit& u) const {
;     ...
;         int wgid = (int)L; { const int q = nwg / NXCD, r = nwg % NXCD, xcd = wgid % NXCD, off = wgid / NXCD; wgid = (xcd < r ? xcd * (q + 1) : r * (q + 1) + (xcd - r) * q) + off; }
;         const int nig = WGM * nN, gid = wgid / nig, fm = gid * WGM, gsz = (nM - fm) < WGM ? (nM - fm) : WGM;
;         u.pm = fm + ((wgid % nig) % gsz); u.pn = (wgid % nig) / gsz; return true;
.Lnorot_win:
	s_ashr_i32 s7, s56, 31
	s_lshr_b32 s7, s7, 29
	s_add_i32 s7, s56, s7
	s_ashr_i32 s17, s7, 3
	s_and_b32 s7, s7, -8
	s_sub_i32 s7, s56, s7
	s_cmp_lt_i32 s7, 0
	s_cselect_b32 s18, s74, 0x130
	s_mul_i32 s7, s18, s7
	s_add_i32 s7, s7, s17
	s_mul_hi_i32 s17, s7, 0x6bca1af3
	s_lshr_b32 s18, s17, 31
	s_ashr_i32 s17, s17, 6
	s_add_i32 s17, s17, s18
	s_lshl_b32 s18, s17, 2
	s_sub_i32 s19, 64, s18
	s_min_i32 s19, s19, 4
	s_mulk_i32 s17, 0x98
	s_sub_i32 s7, s7, s17
	s_lshr_b32 s52, s7, 2
	s_and_b32 s7, s7, 3
	s_add_i32 s54, s7, s18

;     DI bool next(int i, Unit& u) const {
;     ...
;         int wgid = (int)L; { const int q = nwg / NXCD, r = nwg % NXCD, xcd = wgid % NXCD, off = wgid / NXCD; wgid = (xcd < r ? xcd * (q + 1) : r * (q + 1) + (xcd - r) * q) + off; }
;         const int nig = WGM * nN, gid = wgid / nig, fm = gid * WGM, gsz = (nM - fm) < WGM ? (nM - fm) : WGM;
;         u.pm = fm + ((wgid % nig) % gsz); u.pn = (wgid % nig) / gsz; return true;
.LBB0_698:
	s_add_i32 s12, s12, 1
	s_mul_i32 s4, s12, s15
	s_mul_hi_u32 s5, s12, s14
	s_add_i32 s5, s5, s4
	s_mul_i32 s4, s12, s14
	s_add_u32 s50, s4, s24
	s_addc_u32 s51, s5, s62
	v_mov_b64_e32 v[2:3], 0x1600
	v_cmp_lt_i64_e64 s[4:5], s[50:51], v[2:3]
	v_mov_b64_e32 v[2:3], 0x15ff
	v_cmp_gt_i64_e32 vcc, s[50:51], v[2:3]
	s_cbranch_vccnz .LBB0_700
	s_ashr_i32 s18, s50, 31
	s_lshr_b32 s18, s18, 29
	s_add_i32 s18, s50, s18
	s_ashr_i32 s19, s18, 3
	s_and_b32 s18, s18, -8
	s_sub_i32 s18, s50, s18
	s_cmp_lt_i32 s18, 0
	s_movk_i32 s22, 0x2c1
	s_cselect_b32 s22, s22, 0x2c0
	s_mul_i32 s18, s22, s18
	s_add_i32 s18, s18, s19
	s_mul_hi_i32 s19, s18, 0x2e8ba2e9
	s_lshr_b32 s22, s19, 31
	s_ashr_i32 s19, s19, 4
	s_add_i32 s19, s19, s22
	s_lshl_b32 s22, s19, 2
	s_sub_i32 s23, 0x100, s22
	s_min_i32 s23, s23, 4
	s_mulk_i32 s19, 0x58
	s_sub_i32 s18, s18, s19
	s_lshr_b32 s46, s18, 2
	s_and_b32 s18, s18, 3
	s_add_i32 s48, s18, s22
